# v23 + non-temporal loads/stores in the combine chunks (avoid evicting K/V tiles of running attention items from L2)
# baseline (speedup 1.0000x reference)
; DI void phase_combine(const Params& p) {
;   const int lane = threadIdx.x & 63, wave = threadIdx.x >> 6;
;   const unsigned* ofw = (const unsigned*)p.out; const unsigned* obw = (const unsigned*)((const bf16_t*)p.out + (size_t)NTOK * 512);
;   const unsigned* GH = (const unsigned*)(p.ws + WS_GH);
;   bf16_t* OC = (bf16_t*)(p.ws + WS_OCAT);
;   const float w0 = p.hgrn_norm_w[lane * 2], w1 = p.hgrn_norm_w[lane * 2 + 1];
;   for (int tok = blockIdx.x * 8 + wave; tok < NTOK; tok += gridDim.x * 8) {
;     unsigned a[4], b[4], g[4];
; #pragma unroll
;     for (int hh = 0; hh < 4; ++hh) { const size_t idx = ((size_t)tok * 512 + hh * 128 + lane * 2) >> 1; a[hh] = ofw[idx]; b[hh] = obw[idx]; g[hh] = GH[idx]; }
.Lcq_go:
	s_or_b64 exec, exec, s[0:1]
	s_barrier
	s_sub_i32 s3, s12, 0x830
	s_lshl_b32 s3, s3, 7
	s_add_i32 s99, s3, 128
	v_lshrrev_b32_e32 v0, 6, v202
	v_add_u32_e32 v0, s3, v0
	v_and_b32_e32 v4, 0x7e, v203
	v_lshlrev_b32_e32 v1, 2, v4
	global_load_dwordx2 v[2:3], v1, s[46:47]
	v_cmp_lt_i32_e32 vcc, v206, v205
	s_add_u32 s6, s56, 0x4000000
	s_addc_u32 s7, s57, 0
	v_cndmask_b32_e32 v1, v204, v206, vcc
	v_cmp_lt_i32_e32 vcc, v207, v205
	v_lshlrev_b32_e32 v8, 2, v1
	s_add_u32 s8, s58, 0x26000000
	v_cndmask_b32_e32 v1, v204, v207, vcc
	v_cmp_lt_i32_e32 vcc, v211, v205
	v_lshlrev_b32_e32 v9, 2, v1
	s_addc_u32 s9, s59, 0
	v_cndmask_b32_e32 v1, v204, v211, vcc
	v_cmp_lt_i32_e32 vcc, v210, v205
	v_lshlrev_b32_e32 v10, 2, v1
	v_mov_b32_e32 v5, 0
	v_cndmask_b32_e32 v1, v204, v210, vcc
	v_cmp_lt_i32_e32 vcc, v209, v205
	v_lshlrev_b32_e32 v11, 2, v1
	s_mov_b32 s3, 8
	v_cndmask_b32_e32 v1, v204, v209, vcc
	v_cmp_lt_i32_e32 vcc, v208, v205
	v_lshlrev_b32_e32 v12, 2, v1
	s_mov_b64 s[10:11], 0
	v_cndmask_b32_e32 v1, v204, v208, vcc
	v_lshlrev_b32_e32 v13, 2, v1
	v_lshlrev_b32_e32 v4, 1, v4
	s_mov_b64 s[12:13], 0x2a000400
	v_mov_b32_e32 v14, 0x358637bd
	s_mov_b32 s14, 0x800000
	s_mov_b32 s15, 0x2a000000
	s_mov_b32 s16, 0xffff
	v_readfirstlane_b32 s98, v0
	v_ashrrev_i32_e32 v1, 31, v0
	v_lshlrev_b64 v[90:91], 10, v[0:1]
	v_or_b32_e32 v90, v90, v4
	v_lshl_add_u64 v[92:93], s[56:57], 0, v[90:91]
	v_lshl_add_u64 v[94:95], s[6:7], 0, v[90:91]
	v_lshl_add_u64 v[96:97], s[8:9], 0, v[90:91]
	global_load_dword v40, v[92:93], off nt
	global_load_dword v41, v[92:93], off offset:256 nt
	global_load_dword v42, v[92:93], off offset:512 nt
	global_load_dword v43, v[92:93], off offset:768 nt
	global_load_dword v44, v[94:95], off nt
	global_load_dword v45, v[94:95], off offset:256 nt
	global_load_dword v46, v[94:95], off offset:512 nt
	global_load_dword v47, v[94:95], off offset:768 nt
	global_load_dword v48, v[96:97], off nt
	global_load_dword v49, v[96:97], off offset:256 nt
	global_load_dword v50, v[96:97], off offset:512 nt
	global_load_dword v51, v[96:97], off offset:768 nt
	s_waitcnt vmcnt(0)
	s_branch .Lc3_entry

; DI unsigned cvt_pk_bf16(float lo, float hi) { unsigned r; asm("v_cvt_pk_bf16_f32 %0, %1, %2" : "=v"(r) : "v"(lo), "v"(hi)); return r; }
; DI void phase_combine(const Params& p) {
;     ...
;   for (int tok = blockIdx.x * 8 + wave; tok < NTOK; tok += gridDim.x * 8) {
;     unsigned a[4], b[4], g[4];
; #pragma unroll
;     for (int hh = 0; hh < 4; ++hh) { const size_t idx = ((size_t)tok * 512 + hh * 128 + lane * 2) >> 1; a[hh] = ofw[idx]; b[hh] = obw[idx]; g[hh] = GH[idx]; }
; #pragma unroll
;     for (int hh = 0; hh < 4; ++hh) {
;       const float o0 = __uint_as_float(a[hh] << 16) + __uint_as_float(b[hh] << 16), o1 = __uint_as_float(a[hh] & 0xffff0000u) + __uint_as_float(b[hh] & 0xffff0000u);
;       const float ss = wave_sum(o0 * o0 + o1 * o1);
;       const float rstd = rsqrtf(ss * (1.f / 128.f) + EPSN);
;       const float g0 = __uint_as_float(g[hh] << 16), g1 = __uint_as_float(g[hh] & 0xffff0000u);
;       *(unsigned*)(OC + (size_t)tok * 1024 + 512 + hh * 128 + lane * 2) = cvt_pk_bf16(o0 * rstd * w0 * g0, o1 * rstd * w1 * g1);
;     }
.Lc3_entry:
	v_mov_b32_e32 v52, v40
	v_mov_b32_e32 v53, v41
	v_mov_b32_e32 v54, v42
	v_mov_b32_e32 v55, v43
	v_mov_b32_e32 v56, v44
	v_mov_b32_e32 v57, v45
	v_mov_b32_e32 v58, v46
	v_mov_b32_e32 v59, v47
	v_mov_b32_e32 v60, v48
	v_mov_b32_e32 v61, v49
	v_mov_b32_e32 v62, v50
	v_mov_b32_e32 v63, v51
	v_mov_b32_e32 v100, v0
	v_add_u32_e32 v0, s3, v0
	s_add_i32 s98, s98, s3
	s_cmp_lt_i32 s98, s99
	s_cbranch_scc0 .Lc3_noload
	v_ashrrev_i32_e32 v1, 31, v0
	v_lshlrev_b64 v[90:91], 10, v[0:1]
	v_or_b32_e32 v90, v90, v4
	v_lshl_add_u64 v[92:93], s[56:57], 0, v[90:91]
	v_lshl_add_u64 v[94:95], s[6:7], 0, v[90:91]
	v_lshl_add_u64 v[96:97], s[8:9], 0, v[90:91]
	global_load_dword v40, v[92:93], off nt
	global_load_dword v41, v[92:93], off offset:256 nt
	global_load_dword v42, v[92:93], off offset:512 nt
	global_load_dword v43, v[92:93], off offset:768 nt
	global_load_dword v44, v[94:95], off nt
	global_load_dword v45, v[94:95], off offset:256 nt
	global_load_dword v46, v[94:95], off offset:512 nt
	global_load_dword v47, v[94:95], off offset:768 nt
	global_load_dword v48, v[96:97], off nt
	global_load_dword v49, v[96:97], off offset:256 nt
	global_load_dword v50, v[96:97], off offset:512 nt
	global_load_dword v51, v[96:97], off offset:768 nt
.Lc3_noload:
	v_lshlrev_b32_e32 v64, 16, v52
	v_lshlrev_b32_e32 v76, 16, v56
	v_and_b32_e32 v68, 0xffff0000, v52
	v_and_b32_e32 v80, 0xffff0000, v56
	v_add_f32_e32 v64, v64, v76
	v_add_f32_e32 v68, v68, v80
	v_mul_f32_e32 v72, v64, v64
	v_mul_f32_e32 v76, v68, v68
	v_add_f32_e32 v72, v72, v76
	v_lshlrev_b32_e32 v65, 16, v53
	v_lshlrev_b32_e32 v77, 16, v57
	v_and_b32_e32 v69, 0xffff0000, v53
	v_and_b32_e32 v81, 0xffff0000, v57
	v_add_f32_e32 v65, v65, v77
	v_add_f32_e32 v69, v69, v81
	v_mul_f32_e32 v73, v65, v65
	v_mul_f32_e32 v77, v69, v69
	v_add_f32_e32 v73, v73, v77
	v_lshlrev_b32_e32 v66, 16, v54
	v_lshlrev_b32_e32 v78, 16, v58
	v_and_b32_e32 v70, 0xffff0000, v54
	v_and_b32_e32 v82, 0xffff0000, v58
	v_add_f32_e32 v66, v66, v78
	v_add_f32_e32 v70, v70, v82
	v_mul_f32_e32 v74, v66, v66
	v_mul_f32_e32 v78, v70, v70
	v_add_f32_e32 v74, v74, v78
	v_lshlrev_b32_e32 v67, 16, v55
	v_lshlrev_b32_e32 v79, 16, v59
	v_and_b32_e32 v71, 0xffff0000, v55
	v_and_b32_e32 v83, 0xffff0000, v59
	v_add_f32_e32 v67, v67, v79
	v_add_f32_e32 v71, v71, v83
	v_mul_f32_e32 v75, v67, v67
	v_mul_f32_e32 v79, v71, v71
	v_add_f32_e32 v75, v75, v79
	v_ashrrev_i32_e32 v101, 31, v100
	v_lshlrev_b64 v[98:99], 11, v[100:101]
	v_lshl_add_u64 v[98:99], s[58:59], 0, v[98:99]
	v_lshl_add_u64 v[98:99], v[98:99], 0, v[4:5]
	v_lshl_add_u64 v[98:99], v[98:99], 0, s[12:13]
	ds_bpermute_b32 v76, v8, v72
	ds_bpermute_b32 v77, v8, v73
	ds_bpermute_b32 v78, v8, v74
	ds_bpermute_b32 v79, v8, v75
	s_waitcnt lgkmcnt(3)
	v_add_f32_e32 v72, v72, v76
	s_waitcnt lgkmcnt(2)
	v_add_f32_e32 v73, v73, v77
	s_waitcnt lgkmcnt(1)
	v_add_f32_e32 v74, v74, v78
	s_waitcnt lgkmcnt(0)
	v_add_f32_e32 v75, v75, v79
	ds_bpermute_b32 v76, v9, v72
	ds_bpermute_b32 v77, v9, v73
	ds_bpermute_b32 v78, v9, v74
	ds_bpermute_b32 v79, v9, v75
	s_waitcnt lgkmcnt(3)
	v_add_f32_e32 v72, v72, v76
	s_waitcnt lgkmcnt(2)
	v_add_f32_e32 v73, v73, v77
	s_waitcnt lgkmcnt(1)
	v_add_f32_e32 v74, v74, v78
	s_waitcnt lgkmcnt(0)
	v_add_f32_e32 v75, v75, v79
	ds_bpermute_b32 v76, v10, v72
	ds_bpermute_b32 v77, v10, v73
	ds_bpermute_b32 v78, v10, v74
	ds_bpermute_b32 v79, v10, v75
	s_waitcnt lgkmcnt(3)
	v_add_f32_e32 v72, v72, v76
	s_waitcnt lgkmcnt(2)
	v_add_f32_e32 v73, v73, v77
	s_waitcnt lgkmcnt(1)
	v_add_f32_e32 v74, v74, v78
	s_waitcnt lgkmcnt(0)
	v_add_f32_e32 v75, v75, v79
	ds_bpermute_b32 v76, v11, v72
	ds_bpermute_b32 v77, v11, v73
	ds_bpermute_b32 v78, v11, v74
	ds_bpermute_b32 v79, v11, v75
	s_waitcnt lgkmcnt(3)
	v_add_f32_e32 v72, v72, v76
	s_waitcnt lgkmcnt(2)
	v_add_f32_e32 v73, v73, v77
	s_waitcnt lgkmcnt(1)
	v_add_f32_e32 v74, v74, v78
	s_waitcnt lgkmcnt(0)
	v_add_f32_e32 v75, v75, v79
	ds_bpermute_b32 v76, v12, v72
	ds_bpermute_b32 v77, v12, v73
	ds_bpermute_b32 v78, v12, v74
	ds_bpermute_b32 v79, v12, v75
	s_waitcnt lgkmcnt(3)
	v_add_f32_e32 v72, v72, v76
	s_waitcnt lgkmcnt(2)
	v_add_f32_e32 v73, v73, v77
	s_waitcnt lgkmcnt(1)
	v_add_f32_e32 v74, v74, v78
	s_waitcnt lgkmcnt(0)
	v_add_f32_e32 v75, v75, v79
	ds_bpermute_b32 v76, v13, v72
	ds_bpermute_b32 v77, v13, v73
	ds_bpermute_b32 v78, v13, v74
	ds_bpermute_b32 v79, v13, v75
	s_waitcnt lgkmcnt(3)
	v_add_f32_e32 v72, v72, v76
	s_waitcnt lgkmcnt(2)
	v_add_f32_e32 v73, v73, v77
	s_waitcnt lgkmcnt(1)
	v_add_f32_e32 v74, v74, v78
	s_waitcnt lgkmcnt(0)
	v_add_f32_e32 v75, v75, v79
	v_fmamk_f32 v80, v72, 0x3c000000, v14
	v_mul_f32_e32 v76, 0x4b800000, v80
	v_cmp_gt_f32_e32 vcc, s14, v80
	s_nop 1
	v_cndmask_b32_e32 v80, v80, v76, vcc
	v_rsq_f32_e32 v80, v80
	s_nop 0
	v_mul_f32_e32 v76, 0x45800000, v80
	v_cndmask_b32_e32 v80, v80, v76, vcc
	v_mul_f32_e32 v64, v64, v80
	v_mul_f32_e32 v68, v68, v80
	v_mul_f32_e32 v64, v2, v64
	v_mul_f32_e32 v68, v3, v68
	v_lshlrev_b32_e32 v76, 16, v60
	v_and_b32_e32 v72, 0xffff0000, v60
	v_mul_f32_e32 v64, v64, v76
	v_mul_f32_e32 v68, v68, v72
	v_cvt_pk_bf16_f32 v64, v64, v68
	global_store_dword v[98:99], v64, off nt
	v_fmamk_f32 v81, v73, 0x3c000000, v14
	v_mul_f32_e32 v77, 0x4b800000, v81
	v_cmp_gt_f32_e32 vcc, s14, v81
	s_nop 1
	v_cndmask_b32_e32 v81, v81, v77, vcc
	v_rsq_f32_e32 v81, v81
	s_nop 0
	v_mul_f32_e32 v77, 0x45800000, v81
	v_cndmask_b32_e32 v81, v81, v77, vcc
	v_mul_f32_e32 v65, v65, v81
	v_mul_f32_e32 v69, v69, v81
	v_mul_f32_e32 v65, v2, v65
	v_mul_f32_e32 v69, v3, v69
	v_lshlrev_b32_e32 v77, 16, v61
	v_and_b32_e32 v73, 0xffff0000, v61
	v_mul_f32_e32 v65, v65, v77
	v_mul_f32_e32 v69, v69, v73
	v_cvt_pk_bf16_f32 v65, v65, v69
	global_store_dword v[98:99], v65, off offset:256 nt
	v_fmamk_f32 v82, v74, 0x3c000000, v14
	v_mul_f32_e32 v78, 0x4b800000, v82
	v_cmp_gt_f32_e32 vcc, s14, v82
	s_nop 1
	v_cndmask_b32_e32 v82, v82, v78, vcc
	v_rsq_f32_e32 v82, v82
	s_nop 0
	v_mul_f32_e32 v78, 0x45800000, v82
	v_cndmask_b32_e32 v82, v82, v78, vcc
	v_mul_f32_e32 v66, v66, v82
	v_mul_f32_e32 v70, v70, v82
	v_mul_f32_e32 v66, v2, v66
	v_mul_f32_e32 v70, v3, v70
	v_lshlrev_b32_e32 v78, 16, v62
	v_and_b32_e32 v74, 0xffff0000, v62
	v_mul_f32_e32 v66, v66, v78
	v_mul_f32_e32 v70, v70, v74
	v_cvt_pk_bf16_f32 v66, v66, v70
	global_store_dword v[98:99], v66, off offset:512 nt
	v_fmamk_f32 v83, v75, 0x3c000000, v14
	v_mul_f32_e32 v79, 0x4b800000, v83
	v_cmp_gt_f32_e32 vcc, s14, v83
	s_nop 1
	v_cndmask_b32_e32 v83, v83, v79, vcc
	v_rsq_f32_e32 v83, v83
	s_nop 0
	v_mul_f32_e32 v79, 0x45800000, v83
	v_cndmask_b32_e32 v83, v83, v79, vcc
	v_mul_f32_e32 v67, v67, v83
	v_mul_f32_e32 v71, v71, v83
	v_mul_f32_e32 v67, v2, v67
	v_mul_f32_e32 v71, v3, v71
	v_lshlrev_b32_e32 v79, 16, v63
	v_and_b32_e32 v75, 0xffff0000, v63
	v_mul_f32_e32 v67, v67, v79
	v_mul_f32_e32 v71, v71, v75
	v_cvt_pk_bf16_f32 v67, v67, v71
	global_store_dword v[98:99], v67, off offset:768 nt
	s_cmp_lt_i32 s98, s99
	s_cbranch_scc1 .Lc3_loop
	s_branch .LBB0_952
